# RWKV prompt loop: quarter-rate 64-bit address arithmetic replaced by 32-bit offsets against scalar base pointers (loads of next chunk, output store); code placement +8 bytes
# speedup vs baseline: 1.0171x; 1.0004x over previous
.LBB0_1228:
	s_or_b64 exec, exec, s[14:15]
	v_and_b32_e32 v59, 63, v56
	v_lshrrev_b32_e32 v60, 3, v59
	v_ashrrev_i32_e32 v59, 5, v56
	v_and_b32_e32 v93, 7, v56
	v_lshl_add_u32 v56, v63, 2, 0
	v_lshlrev_b32_e32 v63, 1, v63
	v_lshl_add_u32 v61, v67, 2, v56
	v_sub_u32_e32 v56, v56, v63
	v_lshlrev_b32_e32 v63, 1, v67
	v_lshlrev_b32_e32 v71, 8, v62
	v_lshlrev_b32_e32 v62, 7, v62
	v_lshlrev_b32_e32 v67, 2, v66
	v_add3_u32 v109, v56, v63, v62
	s_movk_i32 s24, 0x710
	v_lshl_or_b32 v63, v59, 6, v66
	v_add_u32_e32 v68, 0, v67
	v_mul_lo_u32 v56, v59, s24
	v_lshlrev_b32_e32 v66, 2, v63
	v_lshl_or_b32 v108, v57, 3, v60
	v_mov_b32_e32 v77, 0
	v_lshlrev_b32_e32 v69, 2, v65
	v_add_u32_e32 v62, 0, v56
	v_add_u32_e32 v92, 0, v66
	v_add_u32_e32 v111, v68, v56
	v_and_b32_e32 v56, 32, v174
	s_add_i32 s16, 0, 0x16200
	s_movk_i32 s17, 0xf8f4
	v_lshl_add_u64 v[90:91], s[12:13], 0, v[76:77]
	v_sub_u32_e32 v69, v68, v69
	v_cmp_eq_u32_e64 s[12:13], 0, v56
	v_add_u32_e32 v112, s16, v66
	v_mul_lo_u32 v56, v59, s17
	v_lshl_add_u32 v115, v108, 2, s16
	v_mad_u64_u32 v[94:95], s[16:17], v63, 28, v[92:93]
	v_lshl_add_u32 v113, v59, 7, v69
	v_cmp_gt_i32_e64 s[16:17], 16, v59
	v_add_u32_e32 v95, s3, v59
	v_mul_lo_u32 v59, v89, s24
	v_add_u32_e32 v66, 0, v59
	v_mov_b32_e32 v59, 0x1540
	v_mov_b32_e32 v68, s29
	v_cmp_gt_u32_e32 vcc, 24, v58
	v_add_u32_e32 v110, v62, v67
	v_lshlrev_b32_e32 v67, 5, v58
	v_cndmask_b32_e32 v59, v59, v68, vcc
	v_mov_b32_e32 v68, s28
	v_cmp_gt_u32_e32 vcc, 16, v58
	v_lshlrev_b32_e32 v70, 2, v93
	s_movk_i32 s25, 0xffe4
	v_cndmask_b32_e32 v59, v59, v68, vcc
	v_mov_b32_e32 v68, s5
	v_cmp_gt_i32_e32 vcc, 8, v58
	v_cmp_eq_u32_e64 s[14:15], 0, v65
	v_mul_u32_u24_e32 v65, 12, v93
	v_cndmask_b32_e32 v59, v59, v68, vcc
	v_lshl_add_u32 v58, v58, 3, v59
	v_ashrrev_i32_e32 v59, 31, v58
	v_lshl_add_u64 v[96:97], v[58:59], 1, s[22:23]
	v_mov_b32_e32 v58, 0x140
	v_cndmask_b32_e64 v76, v58, 64, s[18:19]
	v_mov_b32_e32 v58, 0x180
	v_mov_b32_e32 v59, 0x80
	v_cndmask_b32_e64 v98, v58, v59, s[18:19]
	v_mov_b32_e32 v58, 0x1c0
	v_mov_b32_e32 v59, 0xc0
	v_cndmask_b32_e64 v100, v58, v59, s[18:19]
	v_mov_b32_e32 v58, 0x100
	v_cndmask_b32_e64 v102, v58, 0, s[18:19]
	v_lshlrev_b32_e32 v58, 1, v64
	v_mov_b32_e32 v59, v77
	v_lshl_add_u64 v[106:107], s[20:21], 0, v[58:59]
	v_lshlrev_b32_e32 v58, 8, v57
	v_lshlrev_b32_e32 v59, 5, v60
	v_or3_b32 v58, v58, v59, v70
	v_mul_lo_u32 v63, v63, s25
	v_add_u32_e32 v116, 0xe200, v58
	s_movk_i32 s5, 0x7180
	v_lshlrev_b32_e32 v58, 2, v60
	s_mov_b32 s4, 0
	v_add3_u32 v114, 0, v70, v65
	v_mov_b32_e32 v99, v77
	v_mov_b32_e32 v101, v77
	v_mov_b32_e32 v103, v77
	s_waitcnt vmcnt(5)
	v_mov_b32_e32 v104, v85
	v_add3_u32 v117, v65, v70, s5
	v_lshl_or_b32 v118, v57, 5, v58
	v_add_u32_e32 v119, v66, v67
	s_movk_i32 s5, 0x800
	s_movk_i32 s28, 0x2e00
	s_mov_b32 s29, 0x800000
	v_mov_b32_e32 v120, 0x3a27c5ac
	v_add_u32_e32 v121, v94, v63
	v_add_u32_e32 v122, v61, v71
	v_add_u32_e32 v123, v62, v56
	v_mov_b32_e32 v127, v77
	v_mov_b32_e32 v126, v77
	v_mov_b32_e32 v125, v77
	v_mov_b32_e32 v124, v77
	s_nop 0
	s_nop 0
	s_nop 0
	s_nop 0
	s_nop 0
	s_nop 0
	s_load_dwordx2 s[90:91], s[72:73], 0x128
	s_load_dwordx2 s[94:95], s[72:73], 0x120
	s_waitcnt lgkmcnt(0)
	s_add_u32 s92, s90, 0x2800000
	s_addc_u32 s93, s91, 0
	s_add_u32 s90, s90, 0xf700000
	s_addc_u32 s91, s91, 0
	v_subrev_u32_e32 v170, s90, v90
	v_add_u32_e32 v170, v170, v102
	v_lshl_add_u32 v170, v88, 9, v170
	v_subrev_u32_e32 v171, s92, v96
	v_subrev_u32_e32 v178, s94, v106
	s_mov_b32 s100, 0
	s_and_saveexec_b64 s[18:19], s[10:11]
	s_cbranch_execz .LBB0_1230

.LBB0_1230:
	s_or_b64 exec, exec, s[18:19]
	s_add_i32 s30, s4, 1
	s_cmpk_lg_i32 s4, 0x7f
	s_cselect_b64 s[18:19], -1, 0
	s_cmpk_eq_i32 s4, 0x7f
	s_cselect_b64 vcc, -1, 0
	s_waitcnt vmcnt(0)
	v_cndmask_b32_e32 v48, 0, v48, vcc
	s_nor_b64 s[24:25], s[8:9], vcc
	v_cndmask_b32_e32 v49, 0, v49, vcc
	v_cndmask_b32_e32 v50, 0, v50, vcc
	v_cndmask_b32_e32 v51, 0, v51, vcc
	v_cndmask_b32_e32 v52, 0, v52, vcc
	v_cndmask_b32_e32 v53, 0, v53, vcc
	v_cndmask_b32_e32 v54, 0, v54, vcc
	v_cndmask_b32_e32 v55, 0, v55, vcc
	s_and_saveexec_b64 s[22:23], s[24:25]
	s_cbranch_execz .Lrw_noload
	v_lshl_add_u32 v56, s30, 4, v89
	v_cmp_gt_i32_e32 vcc, s5, v56
	v_mov_b32_e32 v55, 0
	v_mov_b32_e32 v54, 0
	v_mov_b32_e32 v53, 0
	v_mov_b32_e32 v52, 0
	v_mov_b32_e32 v51, 0
	v_mov_b32_e32 v50, 0
	v_mov_b32_e32 v49, 0
	v_mov_b32_e32 v48, 0
	s_and_saveexec_b64 s[24:25], vcc
	s_cbranch_execz .LBB0_1248
	v_add_u32_e32 v57, s3, v56
	v_mad_u32_u24 v48, v57, s28, v171
	global_load_dwordx4 v[48:51], v48, s[92:93]
	v_mov_b32_e32 v55, 0
	v_cmp_lt_i32_e32 vcc, 0, v56
	v_mov_b32_e32 v54, 0
	v_mov_b32_e32 v53, 0
	v_mov_b32_e32 v52, 0
	s_and_saveexec_b64 s[26:27], vcc
	s_cbranch_execz .LBB0_1247
	v_add_u32_e32 v52, -1, v57
	v_mad_u32_u24 v52, v52, s28, v171
	global_load_dwordx4 v[52:55], v52, s[92:93]

.LBB0_1234:
	s_or_b64 exec, exec, s[22:23]
	s_waitcnt lgkmcnt(0)
	s_barrier
	s_andn2_b64 vcc, exec, s[18:19]
	s_cbranch_vccnz .LBB0_1236
	v_lshl_add_u32 v56, s30, 13, v170
	global_load_dwordx4 v[32:35], v56, s[90:91]
	global_load_dwordx4 v[36:39], v56, s[90:91] offset:64
	global_load_dwordx4 v[40:43], v56, s[90:91] offset:128
	global_load_dwordx4 v[44:47], v56, s[90:91] offset:192
.LBB0_1236:
	s_nop 0
	s_cmp_eq_u32 s4, 0
	s_cbranch_scc1 .Lrw_skipd
	s_add_i32 s98, s4, -1
	s_xor_b32 s101, s100, 0xe100
	s_cmp_lg_u32 s100, 0
	s_cselect_b32 s97, 0, 64
	v_add_u32_e32 v166, s97, v123
	s_waitcnt lgkmcnt(1)
	ds_read_b128 v[56:59], v94 offset:57856
	ds_read_b128 v[60:63], v94 offset:57872
	ds_read_b128 v[64:67], v94 offset:57888
	ds_read_b128 v[68:71], v94 offset:57904
	s_waitcnt lgkmcnt(3)
	v_add_f32_e32 v56, v56, v57
	v_add_f32_e32 v57, v58, v59
	v_add_f32_e32 v56, v56, v57
	s_waitcnt lgkmcnt(2)
	v_add_f32_e32 v57, v60, v61
	v_add_f32_e32 v58, v62, v63
	v_add_f32_e32 v57, v57, v58
	v_add_f32_e32 v56, v56, v57
	s_waitcnt lgkmcnt(1)
	v_add_f32_e32 v57, v64, v65
	v_add_f32_e32 v58, v66, v67
	v_add_f32_e32 v57, v57, v58
	s_waitcnt lgkmcnt(0)
	v_add_f32_e32 v58, v68, v69
	v_add_f32_e32 v59, v70, v71
	v_add_f32_e32 v58, v58, v59
	v_add_f32_e32 v57, v57, v58
	v_add_f32_e32 v58, v56, v57
	s_nop 1
	v_add_f32_dpp v58, v58, v58 quad_perm:[1,0,3,2] row_mask:0xf bank_mask:0xf bound_ctrl:1
	s_nop 1
	v_add_f32_dpp v58, v58, v58 quad_perm:[2,3,0,1] row_mask:0xf bank_mask:0xf bound_ctrl:1
	s_nop 1
	v_add_f32_dpp v58, v58, v58 row_half_mirror row_mask:0xf bank_mask:0xf bound_ctrl:1
	s_nop 1
	v_add_f32_dpp v58, v58, v58 row_mirror row_mask:0xf bank_mask:0xf bound_ctrl:1
	s_nop 0
	v_readlane_b32 s19, v58, 16
	v_readlane_b32 s23, v58, 48
	v_readlane_b32 s18, v58, 0
	v_readlane_b32 s22, v58, 32
	v_mov_b32_e32 v58, s19
	v_mov_b32_e32 v59, s23
	v_add_f32_e32 v58, s18, v58
	v_add_f32_e32 v59, s22, v59
	v_cndmask_b32_e64 v58, v59, v58, s[12:13]
	v_fmac_f32_e32 v57, 0xbc800000, v58
	v_fmac_f32_e32 v56, 0xbc800000, v58
	v_mul_f32_e32 v58, v57, v57
	v_fmac_f32_e32 v58, v56, v56
	s_nop 1
	v_add_f32_dpp v58, v58, v58 quad_perm:[1,0,3,2] row_mask:0xf bank_mask:0xf bound_ctrl:1
	s_nop 1
	v_add_f32_dpp v58, v58, v58 quad_perm:[2,3,0,1] row_mask:0xf bank_mask:0xf bound_ctrl:1
	s_nop 1
	v_add_f32_dpp v58, v58, v58 row_half_mirror row_mask:0xf bank_mask:0xf bound_ctrl:1
	s_nop 1
	v_add_f32_dpp v58, v58, v58 row_mirror row_mask:0xf bank_mask:0xf bound_ctrl:1
	s_nop 0
	v_readlane_b32 s22, v58, 0
	v_readlane_b32 s24, v58, 16
	v_readlane_b32 s23, v58, 32
	v_readlane_b32 s25, v58, 48
	s_and_saveexec_b64 s[18:19], s[16:17]
	s_cbranch_execz .Lrw_dend
	v_mov_b32_e32 v58, s24
	v_mov_b32_e32 v59, s25
	v_add_f32_e32 v58, s22, v58
	v_add_f32_e32 v59, s23, v59
	v_cndmask_b32_e64 v58, v59, v58, s[12:13]
	v_fmamk_f32 v58, v58, 0x3c800000, v120
	v_mul_f32_e32 v59, 0x4b800000, v58
	v_cmp_gt_f32_e32 vcc, s29, v58
	s_nop 1
	v_cndmask_b32_e32 v58, v58, v59, vcc
	v_rsq_f32_e32 v60, v58
	v_add_u32_e32 v165, s101, v121
	v_mov_b32_e32 v58, v162
	v_mov_b32_e32 v59, v163
	ds_read_b32 v105, v166 offset:57600
	ds_read_b64 v[62:63], v165 offset:37120
	v_mul_f32_e32 v61, 0x45800000, v60
	v_cndmask_b32_e32 v64, v60, v61, vcc
	v_mul_f32_e32 v60, v57, v64
	s_waitcnt lgkmcnt(2)
	v_mov_b32_e32 v61, v59
	s_waitcnt lgkmcnt(1)
	v_pk_mul_f32 v[60:61], v[104:105], v[60:61]
	v_mul_f32_e32 v56, v56, v64
	v_add_f32_e32 v57, v87, v60
	v_add_f32_e32 v57, v57, v61
	s_waitcnt lgkmcnt(0)
	v_mul_f32_e32 v59, v63, v57
	v_mov_b32_e32 v85, v105
	v_mov_b32_e32 v57, v58
	v_pk_mul_f32 v[56:57], v[84:85], v[56:57]
	s_nop 0
	v_add_f32_e32 v56, v86, v56
	v_add_f32_e32 v56, v56, v57
	v_mul_f32_e32 v56, v62, v56
	v_cvt_pk_bf16_f32 v58, v56, v59
	v_lshl_add_u32 v56, s98, 4, v95
	v_lshl_add_u32 v56, v56, 12, v178
	global_store_dword v56, v58, s[94:95] offset:2048

.LBB0_1250:
	s_waitcnt lgkmcnt(0)
	s_barrier
	s_movk_i32 s98, 0x7f
	s_xor_b32 s101, s100, 0xe100
	s_cmp_lg_u32 s100, 0
	s_cselect_b32 s97, 0, 64
	v_add_u32_e32 v166, s97, v123
	s_waitcnt lgkmcnt(1)
	ds_read_b128 v[56:59], v94 offset:57856
	ds_read_b128 v[60:63], v94 offset:57872
	ds_read_b128 v[64:67], v94 offset:57888
	ds_read_b128 v[68:71], v94 offset:57904
	s_waitcnt lgkmcnt(3)
	v_add_f32_e32 v56, v56, v57
	v_add_f32_e32 v57, v58, v59
	v_add_f32_e32 v56, v56, v57
	s_waitcnt lgkmcnt(2)
	v_add_f32_e32 v57, v60, v61
	v_add_f32_e32 v58, v62, v63
	v_add_f32_e32 v57, v57, v58
	v_add_f32_e32 v56, v56, v57
	s_waitcnt lgkmcnt(1)
	v_add_f32_e32 v57, v64, v65
	v_add_f32_e32 v58, v66, v67
	v_add_f32_e32 v57, v57, v58
	s_waitcnt lgkmcnt(0)
	v_add_f32_e32 v58, v68, v69
	v_add_f32_e32 v59, v70, v71
	v_add_f32_e32 v58, v58, v59
	v_add_f32_e32 v57, v57, v58
	v_add_f32_e32 v58, v56, v57
	s_nop 1
	v_add_f32_dpp v58, v58, v58 quad_perm:[1,0,3,2] row_mask:0xf bank_mask:0xf bound_ctrl:1
	s_nop 1
	v_add_f32_dpp v58, v58, v58 quad_perm:[2,3,0,1] row_mask:0xf bank_mask:0xf bound_ctrl:1
	s_nop 1
	v_add_f32_dpp v58, v58, v58 row_half_mirror row_mask:0xf bank_mask:0xf bound_ctrl:1
	s_nop 1
	v_add_f32_dpp v58, v58, v58 row_mirror row_mask:0xf bank_mask:0xf bound_ctrl:1
	s_nop 0
	v_readlane_b32 s19, v58, 16
	v_readlane_b32 s23, v58, 48
	v_readlane_b32 s18, v58, 0
	v_readlane_b32 s22, v58, 32
	v_mov_b32_e32 v58, s19
	v_mov_b32_e32 v59, s23
	v_add_f32_e32 v58, s18, v58
	v_add_f32_e32 v59, s22, v59
	v_cndmask_b32_e64 v58, v59, v58, s[12:13]
	v_fmac_f32_e32 v57, 0xbc800000, v58
	v_fmac_f32_e32 v56, 0xbc800000, v58
	v_mul_f32_e32 v58, v57, v57
	v_fmac_f32_e32 v58, v56, v56
	s_nop 1
	v_add_f32_dpp v58, v58, v58 quad_perm:[1,0,3,2] row_mask:0xf bank_mask:0xf bound_ctrl:1
	s_nop 1
	v_add_f32_dpp v58, v58, v58 quad_perm:[2,3,0,1] row_mask:0xf bank_mask:0xf bound_ctrl:1
	s_nop 1
	v_add_f32_dpp v58, v58, v58 row_half_mirror row_mask:0xf bank_mask:0xf bound_ctrl:1
	s_nop 1
	v_add_f32_dpp v58, v58, v58 row_mirror row_mask:0xf bank_mask:0xf bound_ctrl:1
	s_nop 0
	v_readlane_b32 s22, v58, 0
	v_readlane_b32 s24, v58, 16
	v_readlane_b32 s23, v58, 32
	v_readlane_b32 s25, v58, 48
	s_and_saveexec_b64 s[18:19], s[16:17]
	s_cbranch_execz .Lrw_dend2
	v_mov_b32_e32 v58, s24
	v_mov_b32_e32 v59, s25
	v_add_f32_e32 v58, s22, v58
	v_add_f32_e32 v59, s23, v59
	v_cndmask_b32_e64 v58, v59, v58, s[12:13]
	v_fmamk_f32 v58, v58, 0x3c800000, v120
	v_mul_f32_e32 v59, 0x4b800000, v58
	v_cmp_gt_f32_e32 vcc, s29, v58
	s_nop 1
	v_cndmask_b32_e32 v58, v58, v59, vcc
	v_rsq_f32_e32 v60, v58
	v_add_u32_e32 v165, s101, v121
	v_mov_b32_e32 v58, v162
	v_mov_b32_e32 v59, v163
	ds_read_b32 v105, v166 offset:57600
	ds_read_b64 v[62:63], v165 offset:37120
	v_mul_f32_e32 v61, 0x45800000, v60
	v_cndmask_b32_e32 v64, v60, v61, vcc
	v_mul_f32_e32 v60, v57, v64
	s_waitcnt lgkmcnt(2)
	v_mov_b32_e32 v61, v59
	s_waitcnt lgkmcnt(1)
	v_pk_mul_f32 v[60:61], v[104:105], v[60:61]
	v_mul_f32_e32 v56, v56, v64
	v_add_f32_e32 v57, v87, v60
	v_add_f32_e32 v57, v57, v61
	s_waitcnt lgkmcnt(0)
	v_mul_f32_e32 v59, v63, v57
	v_mov_b32_e32 v85, v105
	v_mov_b32_e32 v57, v58
	v_pk_mul_f32 v[56:57], v[84:85], v[56:57]
	s_nop 0
	v_add_f32_e32 v56, v86, v56
	v_add_f32_e32 v56, v56, v57
	v_mul_f32_e32 v56, v62, v56
	v_cvt_pk_bf16_f32 v58, v56, v59
	v_lshl_add_u32 v56, s98, 4, v95
	v_lshl_add_u32 v56, v56, 12, v178
	global_store_dword v56, v58, s[94:95] offset:2048
